# grid barrier: non-leader workgroups poll the cross-XCD release word directly (no XGEN relay), leader no longer publishes XGEN
# baseline (speedup 1.0000x reference)
; __device__ __forceinline__ unsigned xb_ld(unsigned* p)              { return __hip_atomic_load(p, __ATOMIC_RELAXED, __HIP_MEMORY_SCOPE_AGENT); }
; __device__ __forceinline__ unsigned xb_add(unsigned* p, unsigned v) { return __hip_atomic_fetch_add(p, v, __ATOMIC_RELAXED, __HIP_MEMORY_SCOPE_AGENT); }
; #define XB_SPIN(cond, bar) do { unsigned _sp = 0; while (cond) { __builtin_amdgcn_s_sleep(1); \
;     if ((++_sp & 255u) == 0u) { if (xb_ld(&(bar)[XB_TMO])) break; if (_sp > XB_SPIN_CAP) { atomicAdd(&(bar)[XB_TMO], 1u); break; } } } } while (0)
; __device__ __forceinline__ void xcd_barrier(const XcdBarrier& b, int wv) {
;     ...
;         const unsigned old = xb_add(&bar[XB_XSUB(b.x)], 1u);
;         const unsigned gen = old / nloc;
;         if (old + 1u == (gen + 1u) * nloc) {
;             __builtin_amdgcn_fence(__ATOMIC_RELEASE, "agent");
;             asm volatile("s_waitcnt vmcnt(0)" ::: "memory");
;             const unsigned og = xb_add(&bar[XB_TOP], 1u);
;             const unsigned tg = og / nx;
;             if (og + 1u == (tg + 1u) * nx) xb_add(&bar[XB_TOPGEN], 1u);
;             else XB_SPIN(xb_ld(&bar[XB_TOPGEN]) == tg, bar);
;             __builtin_amdgcn_fence(__ATOMIC_ACQUIRE, "agent");
;             xb_add(&bar[XB_XGEN(b.x)], 1u);
;             asm volatile("s_waitcnt vmcnt(0)" ::: "memory");
;         } else {
;             XB_SPIN(xb_ld(&bar[XB_XGEN(b.x)]) == gen, bar);
.LBB0_614:
	s_or_b64 exec, exec, s[10:11]
	v_cvt_f32_u32_e32 v4, v2
	s_waitcnt vmcnt(0)
	v_readfirstlane_b32 s1, v3
	v_sub_u32_e32 v3, 0, v2
	v_rcp_iflag_f32_e32 v4, v4
	v_add_u32_e32 v5, s1, v1
	v_mul_f32_e32 v4, 0x4f7ffffe, v4
	v_cvt_u32_f32_e32 v4, v4
	v_mul_lo_u32 v1, v3, v4
	v_mul_hi_u32 v1, v4, v1
	v_add_u32_e32 v1, v4, v1
	v_mul_hi_u32 v1, v5, v1
	v_mul_lo_u32 v3, v1, v2
	v_sub_u32_e32 v3, v5, v3
	v_add_u32_e32 v4, 1, v1
	v_cmp_ge_u32_e32 vcc, v3, v2
	s_nop 1
	v_cndmask_b32_e32 v1, v1, v4, vcc
	v_sub_u32_e32 v4, v3, v2
	v_cndmask_b32_e32 v3, v3, v4, vcc
	v_add_u32_e32 v4, 1, v1
	v_cmp_ge_u32_e32 vcc, v3, v2
	v_add_u32_e32 v3, 1, v5
	s_nop 0
	v_cndmask_b32_e32 v1, v1, v4, vcc
	v_mul_lo_u32 v4, v2, v1
	v_add_u32_e32 v2, v4, v2
	v_cmp_ne_u32_e32 vcc, v3, v2
	s_and_saveexec_b64 s[8:9], vcc
	s_xor_b64 s[8:9], exec, s[8:9]
	s_cbranch_execz .LBB0_628
	s_waitcnt lgkmcnt(0)
	v_mov_b32_e32 v0, 0
	s_add_u32 s14, s4, 0x4500
	s_addc_u32 s15, s5, 0
	global_load_dword v0, v0, s[14:15] sc1
	s_waitcnt vmcnt(0)
	v_cmp_eq_u32_e32 vcc, v0, v1
	s_and_saveexec_b64 s[10:11], vcc
	s_cbranch_execz .LBB0_627
	s_add_u32 s12, s4, 0x1200
	s_addc_u32 s13, s5, 0
	s_mov_b32 s1, 1
	s_mov_b64 s[16:17], 0
	v_mov_b32_e32 v0, 0
	s_branch .LBB0_618

; __device__ __forceinline__ unsigned xb_add(unsigned* p, unsigned v) { return __hip_atomic_fetch_add(p, v, __ATOMIC_RELAXED, __HIP_MEMORY_SCOPE_AGENT); }
; __device__ __forceinline__ void xcd_barrier(const XcdBarrier& b, int wv) {
;     ...
;             __builtin_amdgcn_fence(__ATOMIC_ACQUIRE, "agent");
;             xb_add(&bar[XB_XGEN(b.x)], 1u);
;             asm volatile("s_waitcnt vmcnt(0)" ::: "memory");
.LBB0_645:
	s_or_b64 exec, exec, s[4:5]
	s_mov_b64 s[4:5], exec
	v_mbcnt_lo_u32_b32 v0, s4, 0
	v_mbcnt_hi_u32_b32 v0, s5, v0
	v_cmp_eq_u32_e32 vcc, 0, v0
	s_waitcnt vmcnt(0)
	buffer_inv sc1
	s_and_saveexec_b64 s[8:9], vcc
	s_cbranch_execz .LBB0_647
	s_bcnt1_i32_b64 s1, s[4:5]
	v_mov_b32_e32 v0, 0x2000
	v_mov_b32_e32 v1, s1
	s_nop 0

; __device__ __forceinline__ unsigned xb_ld(unsigned* p)              { return __hip_atomic_load(p, __ATOMIC_RELAXED, __HIP_MEMORY_SCOPE_AGENT); }
; __device__ __forceinline__ unsigned xb_add(unsigned* p, unsigned v) { return __hip_atomic_fetch_add(p, v, __ATOMIC_RELAXED, __HIP_MEMORY_SCOPE_AGENT); }
; #define XB_SPIN(cond, bar) do { unsigned _sp = 0; while (cond) { __builtin_amdgcn_s_sleep(1); \
;     if ((++_sp & 255u) == 0u) { if (xb_ld(&(bar)[XB_TMO])) break; if (_sp > XB_SPIN_CAP) { atomicAdd(&(bar)[XB_TMO], 1u); break; } } } } while (0)
; __device__ __forceinline__ void xcd_barrier(const XcdBarrier& b, int wv) {
;     ...
;         const unsigned old = xb_add(&bar[XB_XSUB(b.x)], 1u);
;         const unsigned gen = old / nloc;
;         if (old + 1u == (gen + 1u) * nloc) {
;             __builtin_amdgcn_fence(__ATOMIC_RELEASE, "agent");
;             asm volatile("s_waitcnt vmcnt(0)" ::: "memory");
;             const unsigned og = xb_add(&bar[XB_TOP], 1u);
;             const unsigned tg = og / nx;
;             if (og + 1u == (tg + 1u) * nx) xb_add(&bar[XB_TOPGEN], 1u);
;             else XB_SPIN(xb_ld(&bar[XB_TOPGEN]) == tg, bar);
;             __builtin_amdgcn_fence(__ATOMIC_ACQUIRE, "agent");
;             xb_add(&bar[XB_XGEN(b.x)], 1u);
;             asm volatile("s_waitcnt vmcnt(0)" ::: "memory");
;         } else {
;             XB_SPIN(xb_ld(&bar[XB_XGEN(b.x)]) == gen, bar);
.LBB0_832:
	s_or_b64 exec, exec, s[22:23]
	v_cvt_f32_u32_e32 v5, v3
	s_waitcnt vmcnt(0)
	v_readfirstlane_b32 s7, v4
	v_sub_u32_e32 v4, 0, v3
	v_rcp_iflag_f32_e32 v5, v5
	v_add_u32_e32 v6, s7, v0
	v_mul_f32_e32 v5, 0x4f7ffffe, v5
	v_cvt_u32_f32_e32 v5, v5
	v_mul_lo_u32 v0, v4, v5
	v_mul_hi_u32 v0, v5, v0
	v_add_u32_e32 v0, v5, v0
	v_mul_hi_u32 v0, v6, v0
	v_mul_lo_u32 v4, v0, v3
	v_sub_u32_e32 v4, v6, v4
	v_add_u32_e32 v5, 1, v0
	v_cmp_ge_u32_e32 vcc, v4, v3
	s_nop 1
	v_cndmask_b32_e32 v0, v0, v5, vcc
	v_sub_u32_e32 v5, v4, v3
	v_cndmask_b32_e32 v4, v4, v5, vcc
	v_add_u32_e32 v5, 1, v0
	v_cmp_ge_u32_e32 vcc, v4, v3
	v_add_u32_e32 v4, 1, v6
	s_nop 0
	v_cndmask_b32_e32 v0, v0, v5, vcc
	v_mul_lo_u32 v5, v3, v0
	v_add_u32_e32 v3, v5, v3
	v_cmp_ne_u32_e32 vcc, v4, v3
	s_and_saveexec_b64 s[12:13], vcc
	s_xor_b64 s[20:21], exec, s[12:13]
	s_cbranch_execz .LBB0_846
	s_waitcnt lgkmcnt(0)
	s_add_u32 s26, s18, 0x4500
	s_addc_u32 s27, s19, 0
	global_load_dword v2, v1, s[26:27] sc1
	s_waitcnt vmcnt(0)
	v_cmp_eq_u32_e32 vcc, v2, v0
	s_and_saveexec_b64 s[22:23], vcc
	s_cbranch_execz .LBB0_845
	s_add_u32 s24, s18, 0x1200
	s_addc_u32 s25, s19, 0
	s_mov_b32 s7, 1
	s_mov_b64 s[28:29], 0
	s_branch .LBB0_836

; __device__ __forceinline__ unsigned xb_add(unsigned* p, unsigned v) { return __hip_atomic_fetch_add(p, v, __ATOMIC_RELAXED, __HIP_MEMORY_SCOPE_AGENT); }
; __device__ __forceinline__ void xcd_barrier(const XcdBarrier& b, int wv) {
;     ...
;             __builtin_amdgcn_fence(__ATOMIC_ACQUIRE, "agent");
;             xb_add(&bar[XB_XGEN(b.x)], 1u);
;             asm volatile("s_waitcnt vmcnt(0)" ::: "memory");
.LBB0_863:
	s_or_b64 exec, exec, s[18:19]
	s_mov_b64 s[18:19], exec
	v_mbcnt_lo_u32_b32 v0, s18, 0
	v_mbcnt_hi_u32_b32 v0, s19, v0
	v_cmp_eq_u32_e32 vcc, 0, v0
	s_waitcnt vmcnt(0)
	buffer_inv sc1
	s_and_saveexec_b64 s[22:23], vcc
	s_cbranch_execz .LBB0_865
	s_bcnt1_i32_b64 s7, s[18:19]
	v_mov_b32_e32 v0, s7
	s_nop 0

; __device__ __forceinline__ unsigned xb_ld(unsigned* p)              { return __hip_atomic_load(p, __ATOMIC_RELAXED, __HIP_MEMORY_SCOPE_AGENT); }
; __device__ __forceinline__ unsigned xb_add(unsigned* p, unsigned v) { return __hip_atomic_fetch_add(p, v, __ATOMIC_RELAXED, __HIP_MEMORY_SCOPE_AGENT); }
; #define XB_SPIN(cond, bar) do { unsigned _sp = 0; while (cond) { __builtin_amdgcn_s_sleep(1); \
;     if ((++_sp & 255u) == 0u) { if (xb_ld(&(bar)[XB_TMO])) break; if (_sp > XB_SPIN_CAP) { atomicAdd(&(bar)[XB_TMO], 1u); break; } } } } while (0)
; __device__ __forceinline__ void xcd_barrier(const XcdBarrier& b, int wv) {
;     ...
;         const unsigned old = xb_add(&bar[XB_XSUB(b.x)], 1u);
;         const unsigned gen = old / nloc;
;         if (old + 1u == (gen + 1u) * nloc) {
;             __builtin_amdgcn_fence(__ATOMIC_RELEASE, "agent");
;             asm volatile("s_waitcnt vmcnt(0)" ::: "memory");
;             const unsigned og = xb_add(&bar[XB_TOP], 1u);
;             const unsigned tg = og / nx;
;             if (og + 1u == (tg + 1u) * nx) xb_add(&bar[XB_TOPGEN], 1u);
;             else XB_SPIN(xb_ld(&bar[XB_TOPGEN]) == tg, bar);
;             __builtin_amdgcn_fence(__ATOMIC_ACQUIRE, "agent");
;             xb_add(&bar[XB_XGEN(b.x)], 1u);
;             asm volatile("s_waitcnt vmcnt(0)" ::: "memory");
;         } else {
;             XB_SPIN(xb_ld(&bar[XB_XGEN(b.x)]) == gen, bar);
.LBB0_1198:
	s_or_b64 exec, exec, s[22:23]
	v_cvt_f32_u32_e32 v5, v3
	s_waitcnt vmcnt(0)
	v_readfirstlane_b32 s7, v4
	v_sub_u32_e32 v4, 0, v3
	v_rcp_iflag_f32_e32 v5, v5
	v_add_u32_e32 v6, s7, v0
	v_mul_f32_e32 v5, 0x4f7ffffe, v5
	v_cvt_u32_f32_e32 v5, v5
	v_mul_lo_u32 v0, v4, v5
	v_mul_hi_u32 v0, v5, v0
	v_add_u32_e32 v0, v5, v0
	v_mul_hi_u32 v0, v6, v0
	v_mul_lo_u32 v4, v0, v3
	v_sub_u32_e32 v4, v6, v4
	v_add_u32_e32 v5, 1, v0
	v_cmp_ge_u32_e32 vcc, v4, v3
	s_nop 1
	v_cndmask_b32_e32 v0, v0, v5, vcc
	v_sub_u32_e32 v5, v4, v3
	v_cndmask_b32_e32 v4, v4, v5, vcc
	v_add_u32_e32 v5, 1, v0
	v_cmp_ge_u32_e32 vcc, v4, v3
	v_add_u32_e32 v4, 1, v6
	s_nop 0
	v_cndmask_b32_e32 v0, v0, v5, vcc
	v_mul_lo_u32 v5, v3, v0
	v_add_u32_e32 v3, v5, v3
	v_cmp_ne_u32_e32 vcc, v4, v3
	s_and_saveexec_b64 s[12:13], vcc
	s_xor_b64 s[20:21], exec, s[12:13]
	s_cbranch_execz .LBB0_1212
	s_waitcnt lgkmcnt(0)
	s_add_u32 s26, s18, 0x4500
	s_addc_u32 s27, s19, 0
	global_load_dword v2, v1, s[26:27] sc1
	s_waitcnt vmcnt(0)
	v_cmp_eq_u32_e32 vcc, v2, v0
	s_and_saveexec_b64 s[22:23], vcc
	s_cbranch_execz .LBB0_1211
	s_add_u32 s24, s18, 0x1200
	s_addc_u32 s25, s19, 0
	s_mov_b32 s7, 1
	s_mov_b64 s[34:35], 0
	s_branch .LBB0_1202

; __device__ __forceinline__ unsigned xb_add(unsigned* p, unsigned v) { return __hip_atomic_fetch_add(p, v, __ATOMIC_RELAXED, __HIP_MEMORY_SCOPE_AGENT); }
; __device__ __forceinline__ void xcd_barrier(const XcdBarrier& b, int wv) {
;     ...
;             __builtin_amdgcn_fence(__ATOMIC_ACQUIRE, "agent");
;             xb_add(&bar[XB_XGEN(b.x)], 1u);
;             asm volatile("s_waitcnt vmcnt(0)" ::: "memory");
.LBB0_1721:
	s_or_b64 exec, exec, s[18:19]
	s_mov_b64 s[18:19], exec
	v_mbcnt_lo_u32_b32 v0, s18, 0
	v_mbcnt_hi_u32_b32 v0, s19, v0
	v_cmp_eq_u32_e32 vcc, 0, v0
	s_waitcnt vmcnt(0)
	buffer_inv sc1
	s_and_saveexec_b64 s[20:21], vcc
	s_cbranch_execz .LBB0_1723
	s_bcnt1_i32_b64 s7, s[18:19]
	v_mov_b32_e32 v0, s7
	s_nop 0

; __device__ __forceinline__ unsigned xb_add(unsigned* p, unsigned v) { return __hip_atomic_fetch_add(p, v, __ATOMIC_RELAXED, __HIP_MEMORY_SCOPE_AGENT); }
; __device__ __forceinline__ void xcd_barrier(const XcdBarrier& b, int wv) {
;     ...
;             xb_add(&bar[XB_XGEN(b.x)], 1u);
.LBB0_2682:
	s_bcnt1_i32_b64 s7, s[18:19]
	v_mov_b32_e32 v0, s7
	s_nop 0
	s_getpc_b64 s[98:99]
